# stick-breaking inner loop: softplus/log-sigmoid block rewritten with packed f32 add/fma/mul, cumsum MFMA result kept apart (same per-element ops)
# baseline (speedup 1.0000x reference)
.LBB0_304:
	s_waitcnt vmcnt(0)
	v_mfma_f32_32x32x16_bf16 v[34:49], v[34:37], v[58:61], 0
	s_min_u32 s4, s92, 1
	s_lshl_b32 s40, s4, 5
	ds_write_b128 v144, v[122:125]
	ds_write_b128 v144, v[118:121] offset:16
	ds_write_b128 v144, v[106:109] offset:32
	ds_write_b128 v144, v[102:105] offset:48
	v_subrev_u32_e32 v102, s40, v147
	v_subrev_u32_e32 v126, s40, v133
	v_ashrrev_i32_e32 v103, 31, v102
	ds_read_b64_tr_b16 v[86:87], v145
	ds_read_b64_tr_b16 v[88:89], v145 offset:1024
	ds_read_b64_tr_b16 v[100:101], v145 offset:1088
	ds_read_b64_tr_b16 v[98:99], v145 offset:64
	ds_read_b64_tr_b16 v[90:91], v145 offset:2048
	ds_read_b64_tr_b16 v[92:93], v145 offset:3072
	ds_read_b64_tr_b16 v[96:97], v145 offset:3136
	ds_read_b64_tr_b16 v[94:95], v145 offset:2112
	v_mfma_f32_32x32x16_bf16 v[34:49], v[82:85], v[62:65], v[34:49]
	v_lshlrev_b64 v[82:83], 7, v[126:127]
	v_lshl_add_u64 v[104:105], v[136:137], 0, v[82:83]
	v_lshlrev_b64 v[82:83], 7, v[102:103]
	v_lshl_add_u64 v[122:123], v[138:139], 0, v[82:83]
	global_load_dwordx4 v[82:85], v[104:105], off
	s_cmp_lg_u32 s78, 0
	s_cselect_b64 s[68:69], -1, 0
	v_mfma_f32_32x32x16_bf16 v[34:49], v[78:81], v[66:69], v[34:49]
	global_load_dwordx4 v[78:81], v[104:105], off offset:32
	global_load_dwordx4 v[110:113], v[104:105], off offset:64
	global_load_dwordx4 v[114:117], v[104:105], off offset:96
	s_nop 0
	global_load_dwordx4 v[102:105], v[122:123], off offset:48
	global_load_dwordx4 v[106:109], v[122:123], off offset:32
	global_load_dwordx4 v[118:121], v[122:123], off offset:16
	s_nop 0
	global_load_dwordx4 v[122:125], v[122:123], off
	s_or_b64 vcc, s[10:11], s[68:69]
	s_or_b64 s[40:41], s[12:13], s[68:69]
	s_or_b64 s[42:43], s[14:15], s[68:69]
	s_or_b64 s[44:45], s[8:9], s[68:69]
	s_or_b64 s[46:47], s[16:17], s[68:69]
	s_or_b64 s[48:49], s[18:19], s[68:69]
	v_mfma_f32_32x32x16_bf16 v[34:49], v[74:77], v[70:73], v[34:49]
	s_or_b64 s[50:51], s[20:21], s[68:69]
	s_or_b64 s[52:53], s[22:23], s[68:69]
	s_or_b64 s[54:55], s[24:25], s[68:69]
	s_or_b64 s[56:57], s[26:27], s[68:69]
	s_or_b64 s[58:59], s[28:29], s[68:69]
	s_or_b64 s[60:61], s[30:31], s[68:69]
	s_or_b64 s[62:63], s[34:35], s[68:69]
	s_nop 4
	s_or_b64 s[64:65], s[36:37], s[68:69]
	s_or_b64 s[66:67], s[38:39], s[68:69]
	s_or_b64 s[68:69], s[6:7], s[68:69]
	v_mul_f32_e64 v150, |v34|, s88
	v_mul_f32_e64 v151, |v35|, s88
	v_mul_f32_e64 v152, |v36|, s88
	v_mul_f32_e64 v153, |v37|, s88
	v_mul_f32_e64 v154, |v38|, s88
	v_mul_f32_e64 v155, |v39|, s88
	v_mul_f32_e64 v156, |v40|, s88
	v_mul_f32_e64 v157, |v41|, s88
	v_mul_f32_e64 v158, |v42|, s88
	v_mul_f32_e64 v159, |v43|, s88
	v_mul_f32_e64 v160, |v44|, s88
	v_mul_f32_e64 v161, |v45|, s88
	v_mul_f32_e64 v162, |v46|, s88
	v_mul_f32_e64 v163, |v47|, s88
	v_mul_f32_e64 v164, |v48|, s88
	v_mul_f32_e64 v165, |v49|, s88
	v_exp_f32_e32 v150, v150
	v_exp_f32_e32 v151, v151
	v_exp_f32_e32 v152, v152
	v_exp_f32_e32 v153, v153
	v_exp_f32_e32 v154, v154
	v_exp_f32_e32 v155, v155
	v_exp_f32_e32 v156, v156
	v_exp_f32_e32 v157, v157
	v_exp_f32_e32 v158, v158
	v_exp_f32_e32 v159, v159
	v_exp_f32_e32 v160, v160
	v_exp_f32_e32 v161, v161
	v_exp_f32_e32 v162, v162
	v_exp_f32_e32 v163, v163
	v_exp_f32_e32 v164, v164
	v_exp_f32_e32 v165, v165
	v_mov_b32_e32 v178, 1.0
	v_mov_b32_e32 v126, 0x3f317218
	v_pk_add_f32 v[150:151], v[150:151], v[178:179] op_sel_hi:[1,0]
	v_pk_add_f32 v[152:153], v[152:153], v[178:179] op_sel_hi:[1,0]
	v_pk_add_f32 v[154:155], v[154:155], v[178:179] op_sel_hi:[1,0]
	v_pk_add_f32 v[156:157], v[156:157], v[178:179] op_sel_hi:[1,0]
	v_pk_add_f32 v[158:159], v[158:159], v[178:179] op_sel_hi:[1,0]
	v_pk_add_f32 v[160:161], v[160:161], v[178:179] op_sel_hi:[1,0]
	v_pk_add_f32 v[162:163], v[162:163], v[178:179] op_sel_hi:[1,0]
	v_pk_add_f32 v[164:165], v[164:165], v[178:179] op_sel_hi:[1,0]
	v_log_f32_e32 v150, v150
	v_log_f32_e32 v151, v151
	v_log_f32_e32 v152, v152
	v_log_f32_e32 v153, v153
	v_log_f32_e32 v154, v154
	v_log_f32_e32 v155, v155
	v_log_f32_e32 v156, v156
	v_log_f32_e32 v157, v157
	v_log_f32_e32 v158, v158
	v_log_f32_e32 v159, v159
	v_log_f32_e32 v160, v160
	v_log_f32_e32 v161, v161
	v_log_f32_e32 v162, v162
	v_log_f32_e32 v163, v163
	v_log_f32_e32 v164, v164
	v_log_f32_e32 v165, v165
	v_max_f32_e32 v166, 0, v34
	v_max_f32_e32 v167, 0, v35
	v_max_f32_e32 v168, 0, v36
	v_max_f32_e32 v169, 0, v37
	v_max_f32_e32 v170, 0, v38
	v_max_f32_e32 v171, 0, v39
	v_max_f32_e32 v172, 0, v40
	v_max_f32_e32 v173, 0, v41
	v_max_f32_e32 v174, 0, v42
	v_max_f32_e32 v175, 0, v43
	v_max_f32_e32 v176, 0, v44
	v_max_f32_e32 v177, 0, v45
	v_max_f32_e32 v74, 0, v46
	v_max_f32_e32 v75, 0, v47
	v_max_f32_e32 v76, 0, v48
	v_max_f32_e32 v77, 0, v49
	v_pk_fma_f32 v[166:167], v[126:127], v[150:151], v[166:167] op_sel_hi:[0,1,1]
	v_pk_fma_f32 v[168:169], v[126:127], v[152:153], v[168:169] op_sel_hi:[0,1,1]
	v_pk_fma_f32 v[170:171], v[126:127], v[154:155], v[170:171] op_sel_hi:[0,1,1]
	v_pk_fma_f32 v[172:173], v[126:127], v[156:157], v[172:173] op_sel_hi:[0,1,1]
	v_pk_fma_f32 v[174:175], v[126:127], v[158:159], v[174:175] op_sel_hi:[0,1,1]
	v_pk_fma_f32 v[176:177], v[126:127], v[160:161], v[176:177] op_sel_hi:[0,1,1]
	v_pk_fma_f32 v[74:75], v[126:127], v[162:163], v[74:75] op_sel_hi:[0,1,1]
	v_pk_fma_f32 v[76:77], v[126:127], v[164:165], v[76:77] op_sel_hi:[0,1,1]
	v_cndmask_b32_e64 v150, 0, -v166, s[68:69]
	v_cndmask_b32_e64 v151, 0, -v167, vcc
	v_cndmask_b32_e64 v152, 0, -v168, s[40:41]
	v_cndmask_b32_e64 v153, 0, -v169, s[42:43]
	v_cndmask_b32_e64 v154, 0, -v170, s[44:45]
	v_cndmask_b32_e64 v155, 0, -v171, s[46:47]
	v_cndmask_b32_e64 v156, 0, -v172, s[48:49]
	v_cndmask_b32_e64 v157, 0, -v173, s[50:51]
	v_cndmask_b32_e64 v158, 0, -v174, s[52:53]
	v_cndmask_b32_e64 v159, 0, -v175, s[54:55]
	v_cndmask_b32_e64 v160, 0, -v176, s[56:57]
	v_cndmask_b32_e64 v161, 0, -v177, s[58:59]
	v_cndmask_b32_e64 v162, 0, -v74, s[60:61]
	v_cndmask_b32_e64 v163, 0, -v75, s[62:63]
	v_cndmask_b32_e64 v164, 0, -v76, s[64:65]
	v_cndmask_b32_e64 v165, 0, -v77, s[66:67]
	v_pk_add_f32 v[34:35], v[34:35], v[166:167] neg_lo:[0,1] neg_hi:[0,1]
	v_pk_add_f32 v[36:37], v[36:37], v[168:169] neg_lo:[0,1] neg_hi:[0,1]
	v_pk_add_f32 v[38:39], v[38:39], v[170:171] neg_lo:[0,1] neg_hi:[0,1]
	v_pk_add_f32 v[40:41], v[40:41], v[172:173] neg_lo:[0,1] neg_hi:[0,1]
	v_pk_add_f32 v[42:43], v[42:43], v[174:175] neg_lo:[0,1] neg_hi:[0,1]
	v_pk_add_f32 v[44:45], v[44:45], v[176:177] neg_lo:[0,1] neg_hi:[0,1]
	v_pk_add_f32 v[46:47], v[46:47], v[74:75] neg_lo:[0,1] neg_hi:[0,1]
	v_pk_add_f32 v[48:49], v[48:49], v[76:77] neg_lo:[0,1] neg_hi:[0,1]
	v_cndmask_b32_e64 v34, v146, v34, s[68:69]
	v_cndmask_b32_e64 v35, v146, v35, vcc
	v_cndmask_b32_e64 v36, v146, v36, s[40:41]
	v_cndmask_b32_e64 v37, v146, v37, s[42:43]
	v_cndmask_b32_e64 v38, v146, v38, s[44:45]
	v_cndmask_b32_e64 v39, v146, v39, s[46:47]
	v_cndmask_b32_e64 v40, v146, v40, s[48:49]
	v_cndmask_b32_e64 v41, v146, v41, s[50:51]
	v_cndmask_b32_e64 v42, v146, v42, s[52:53]
	v_cndmask_b32_e64 v43, v146, v43, s[54:55]
	v_cndmask_b32_e64 v44, v146, v44, s[56:57]
	v_cndmask_b32_e64 v45, v146, v45, s[58:59]
	v_cndmask_b32_e64 v46, v146, v46, s[60:61]
	v_cndmask_b32_e64 v47, v146, v47, s[62:63]
	v_cndmask_b32_e64 v48, v146, v48, s[64:65]
	v_cndmask_b32_e64 v49, v146, v49, s[66:67]
	v_cvt_pk_f16_f32 v166, v150, v151
	v_cvt_pk_f16_f32 v167, v152, v153
	v_cvt_pk_f16_f32 v168, v154, v155
	v_cvt_pk_f16_f32 v169, v156, v157
	v_cvt_pk_f16_f32 v170, v158, v159
	v_cvt_pk_f16_f32 v171, v160, v161
	v_cvt_pk_f16_f32 v172, v162, v163
	v_cvt_pk_f16_f32 v173, v164, v165
	v_add_f32_e32 v149, 0, v150
	v_add_f32_e32 v149, v151, v149
	v_add_f32_e32 v149, v152, v149
	v_add_f32_e32 v149, v153, v149
	v_add_f32_e32 v149, v154, v149
	v_add_f32_e32 v149, v155, v149
	v_add_f32_e32 v149, v156, v149
	v_add_f32_e32 v149, v157, v149
	v_add_f32_e32 v149, v158, v149
	v_add_f32_e32 v149, v159, v149
	v_add_f32_e32 v149, v160, v149
	v_add_f32_e32 v149, v161, v149
	v_add_f32_e32 v149, v162, v149
	v_add_f32_e32 v149, v163, v149
	v_add_f32_e32 v149, v164, v149
	v_add_f32_e32 v149, v165, v149
	v_mfma_f32_32x32x16_f16 v[150:165], v[50:53], v[166:169], 0
	v_mov_b32_e32 v178, 0x3fb8aa3b
	v_mfma_f32_32x32x16_f16 v[150:165], v[54:57], v[170:173], v[150:165]
	s_nop 7
	s_nop 7
	v_pk_add_f32 v[34:35], v[150:151], v[34:35]
	v_pk_add_f32 v[36:37], v[152:153], v[36:37]
	v_pk_add_f32 v[38:39], v[154:155], v[38:39]
	v_pk_add_f32 v[40:41], v[156:157], v[40:41]
	v_pk_add_f32 v[42:43], v[158:159], v[42:43]
	v_pk_add_f32 v[44:45], v[160:161], v[44:45]
	v_pk_add_f32 v[46:47], v[162:163], v[46:47]
	v_pk_add_f32 v[48:49], v[164:165], v[48:49]
	v_pk_add_f32 v[34:35], v[148:149], v[34:35] op_sel_hi:[0,1]
	v_pk_add_f32 v[36:37], v[148:149], v[36:37] op_sel_hi:[0,1]
	v_pk_add_f32 v[38:39], v[148:149], v[38:39] op_sel_hi:[0,1]
	v_pk_add_f32 v[40:41], v[148:149], v[40:41] op_sel_hi:[0,1]
	v_pk_add_f32 v[42:43], v[148:149], v[42:43] op_sel_hi:[0,1]
	v_pk_add_f32 v[44:45], v[148:149], v[44:45] op_sel_hi:[0,1]
	v_pk_add_f32 v[46:47], v[148:149], v[46:47] op_sel_hi:[0,1]
	v_pk_add_f32 v[48:49], v[148:149], v[48:49] op_sel_hi:[0,1]
	v_pk_mul_f32 v[34:35], v[178:179], v[34:35] op_sel_hi:[0,1]
	v_pk_mul_f32 v[36:37], v[178:179], v[36:37] op_sel_hi:[0,1]
	v_pk_mul_f32 v[38:39], v[178:179], v[38:39] op_sel_hi:[0,1]
	v_pk_mul_f32 v[40:41], v[178:179], v[40:41] op_sel_hi:[0,1]
	v_pk_mul_f32 v[42:43], v[178:179], v[42:43] op_sel_hi:[0,1]
	v_pk_mul_f32 v[44:45], v[178:179], v[44:45] op_sel_hi:[0,1]
	v_pk_mul_f32 v[46:47], v[178:179], v[46:47] op_sel_hi:[0,1]
	v_pk_mul_f32 v[48:49], v[178:179], v[48:49] op_sel_hi:[0,1]
	v_exp_f32_e32 v34, v34
	v_exp_f32_e32 v35, v35
	v_exp_f32_e32 v36, v36
	v_exp_f32_e32 v37, v37
	v_exp_f32_e32 v38, v38
	v_exp_f32_e32 v39, v39
	v_exp_f32_e32 v40, v40
	v_exp_f32_e32 v41, v41
	v_cvt_pk_bf16_f32 v34, v34, v35
	v_cvt_pk_bf16_f32 v35, v36, v37
	v_cvt_pk_bf16_f32 v36, v38, v39
	v_cvt_pk_bf16_f32 v37, v40, v41
	s_waitcnt lgkmcnt(6)
	s_nop 1
	v_mfma_f32_32x32x16_bf16 v[2:17], v[86:89], v[34:37], v[2:17]
	s_waitcnt lgkmcnt(4)
	v_mfma_f32_32x32x16_bf16 v[18:33], v[98:101], v[34:37], v[18:33]
	ds_bpermute_b32 v174, v143, v149
	v_exp_f32_e32 v42, v42
	v_exp_f32_e32 v43, v43
	v_exp_f32_e32 v44, v44
	v_exp_f32_e32 v45, v45
	v_exp_f32_e32 v46, v46
	v_exp_f32_e32 v47, v47
	v_exp_f32_e32 v48, v48
	v_exp_f32_e32 v49, v49
	s_waitcnt lgkmcnt(0)
	v_add_f32_e32 v175, v149, v174
	v_cvt_pk_bf16_f32 v34, v42, v43
	v_cvt_pk_bf16_f32 v35, v44, v45
	v_cvt_pk_bf16_f32 v36, v46, v47
	v_cvt_pk_bf16_f32 v37, v48, v49
	v_add_f32_e32 v148, v148, v175
	v_cmp_gt_f32_e32 vcc, s89, v148
	v_mfma_f32_32x32x16_bf16 v[2:17], v[90:93], v[34:37], v[2:17]
	s_cmp_lg_u64 vcc, exec
	s_cselect_b64 s[4:5], -1, 0
	s_add_i32 s92, s92, -1
	s_cmp_lg_u32 s91, s78
	s_cselect_b64 s[40:41], -1, 0
	s_and_b64 s[4:5], s[40:41], s[4:5]
	s_waitcnt vmcnt(4)
	v_mov_b64_e32 v[74:75], v[114:115]
	v_mfma_f32_32x32x16_bf16 v[18:33], v[94:97], v[34:37], v[18:33]
	v_mov_b64_e32 v[34:35], v[82:83]
	v_mov_b64_e32 v[36:37], v[84:85]
	v_mov_b64_e32 v[84:85], v[80:81]
	v_mov_b64_e32 v[82:83], v[78:79]
	v_mov_b64_e32 v[78:79], v[110:111]
	v_subrev_u32_e32 v147, 32, v147
	v_subrev_u32_e32 v133, 32, v133
	s_add_i32 s78, s78, 1
	s_and_b64 vcc, exec, s[4:5]
	v_mov_b64_e32 v[80:81], v[112:113]
	v_mov_b64_e32 v[76:77], v[116:117]
	s_cbranch_vccnz .LBB0_304
	v_mov_b32_e32 v133, v127
	v_lshl_add_u64 v[34:35], v[134:135], 0, v[132:133]
	v_cvt_pk_bf16_f32 v2, v2, v3
	v_cvt_pk_bf16_f32 v3, v4, v5
	v_cvt_pk_bf16_f32 v4, v18, v19
	v_cvt_pk_bf16_f32 v5, v20, v21
	global_store_dwordx2 v[34:35], v[2:3], off
	global_store_dwordx2 v[34:35], v[4:5], off offset:64
	v_cvt_pk_bf16_f32 v2, v6, v7
	v_cvt_pk_bf16_f32 v3, v8, v9
	v_cvt_pk_bf16_f32 v4, v22, v23
	v_cvt_pk_bf16_f32 v5, v24, v25
	global_store_dwordx2 v[34:35], v[2:3], off offset:16
	global_store_dwordx2 v[34:35], v[4:5], off offset:80
	v_cvt_pk_bf16_f32 v2, v10, v11
	v_cvt_pk_bf16_f32 v3, v12, v13
	v_cvt_pk_bf16_f32 v4, v26, v27
	v_cvt_pk_bf16_f32 v5, v28, v29
	s_add_i32 s90, s90, s87
	global_store_dwordx2 v[34:35], v[2:3], off offset:32
	global_store_dwordx2 v[34:35], v[4:5], off offset:96
	v_cvt_pk_bf16_f32 v2, v14, v15
	v_cvt_pk_bf16_f32 v3, v16, v17
	v_cvt_pk_bf16_f32 v4, v30, v31
	v_cvt_pk_bf16_f32 v5, v32, v33
	s_cmpk_lt_i32 s90, 0x2000
	global_store_dwordx2 v[34:35], v[2:3], off offset:48
	global_store_dwordx2 v[34:35], v[4:5], off offset:112
	s_cbranch_scc1 .LBB0_303
